# P1 full-line store transform + static s_setprio 1 for waves 4-7 during attention
# speedup vs baseline: 1.0021x; 1.0021x over previous
; #define LAS __attribute__((address_space(3)))
; __device__ __forceinline__ void attn_prompt(Frame& F, int b, int h, int qb, float lam, float mshift) {
;     int tid = F.tid; asm volatile("" : "+v"(tid));
;     const int lane = tid & 63, w = F.wave, r32 = lane & 31, hi = lane >> 5;
;     const int m = w >> 2, rb = w & 3;
;     const int NT = 2 * qb + 2;
;     const size_t qrow0 = (size_t)b * SEQ + 128 * qb;
;     const int qpw = 128 * qb + 32 * rb, cw = qpw >> 6;
;     const bool vis = (cw == NT - 1);
;     LAS unsigned char* L = F.lds;
;     LAS float* TB = (LAS float*)(L + P_TB); LAS float* WSF = (LAS float*)(L + P_WS) + w * 64;
;     const bf16* QB = (const bf16*)(F.ws + WS_Q); const bf16* ZB = (const bf16*)(F.ws + WS_ZB); bf16* YAB = (bf16*)(F.ws + WS_YAB);
;     const bf16* Kt = (const bf16*)(F.ws + WS_K) + ((size_t)b * SEQ) * DM + h * 128; const bf16* Vt = (const bf16*)(F.ws + WS_V) + ((size_t)b * SEQ) * DM + h * 128;
; __global__ void __launch_bounds__(NWAVES * 64, 2) skel_fwd(Args args) {
;     ...
;         const int vcu = F.vcu;
;         for (int rep = 0; rep < (PROBE_DUP == 2 ? 2 : 1); ++rep)
;         for (int i = vcu; i < 512; i += F.G) lru_unit(F, i >> 3, i & 7);
;         {
;             const bool bal = (F.G == 256);
;             const int x = vcu >> 5, j = vcu & 31, s = j & 7, srnd = 4 * ((vcu >> 3) & 3);
;             const int nU = bal ? (PROBE_DUP == 4 ? 32 : 16) : (4096 + F.G - 1) / F.G;
;             for (int u = 0; u < nU; ++u) {
;                 const int si = bal ? vcu : vcu + u * F.G;
;                 if (bal ? (u == srnd || (PROBE_DUP == 3 && u == srnd + 1)) : (si < 256)) attn_unit<true>(F, si >> 3, si & 7, 0, 0.f, 0.f);
;                 int bh, qb;
;                 if (bal) { bh = 32 * x + 4 * ((u & 15) >> 1) + (j >> 3); qb = (u & 1) ? s : 15 - s; }
;                 else { const int p = vcu + u * F.G; if (p >= 4096) break; bh = p >> 4; qb = p & 15; }
;                 attn_prompt(F, bh >> 3, bh & 7, qb, 0.f, 0.f);
.LBB0_446:
	s_cmp_lt_i32 s62, 1
	s_cbranch_scc1 .LBB0_532
	s_cmp_lt_u32 s97, 4
	s_cbranch_scc1 .Lprio_done
	s_setprio 1
.Lprio_done:
	s_lshr_b32 s0, s96, 1
	s_and_b32 s0, s0, 12
	v_writelane_b32 v255, s0, 23
	s_and_b32 s0, s96, 0xffffffe0
	s_bfe_u32 s1, s96, 0x20003
	s_and_b32 s63, s96, 7
	s_or_b32 s0, s1, s0
	v_writelane_b32 v255, s0, 12
	s_xor_b32 s0, s63, 15
	v_writelane_b32 v255, s0, 14
	s_lshl_b32 s4, s97, 8
	v_readlane_b32 s5, v255, 7
	s_bfe_u32 s2, s5, 0x10007
	s_add_i32 s68, s4, 0
	s_lshr_b32 s0, s5, 8
	s_lshr_b32 s1, s5, 7
	s_bfe_u32 s3, s5, 0x10006
	s_lshl_b32 s67, s2, 5
	s_add_i32 s68, s68, 0x10400
	s_add_u32 s24, s74, 0x1ac00000
	s_addc_u32 s25, s75, 0
	s_add_u32 s26, s74, 0x33800000
	s_addc_u32 s27, s75, 0
	s_lshl_b32 s4, s3, 13
	s_lshl_b32 s69, s0, 6
	s_add_i32 s4, s4, 0
	v_writelane_b32 v255, s4, 25
	s_add_u32 s4, s72, 0x30880000
	s_addc_u32 s77, s73, 0
	s_add_u32 s78, s72, 0x31080000
	v_writelane_b32 v255, s4, 17
	s_addc_u32 s79, s73, 0
	s_lshl_b32 s4, s3, 7
	s_add_i32 s81, s4, 0
	s_lshl_b32 s80, s3, 5
	s_add_i32 s81, s81, 0x10000
	s_and_b32 s4, 64, s5
	s_cmp_eq_u32 s3, 0
	s_cselect_b64 s[28:29], -1, 0
	s_cmp_lg_u32 s4, 0
	s_cselect_b64 s[30:31], -1, 0
	s_lshl_b32 s1, s1, 14
	s_add_i32 s82, s1, 0
	s_cmpk_lt_u32 s5, 0x100
	s_cselect_b64 s[36:37], -1, 0
	s_cmpk_gt_u32 s5, 0xff
	s_cselect_b64 s[40:41], -1, 0
	s_cmp_eq_u32 s0, 1
	s_cselect_b64 s[42:43], -1, 0
	s_lshl_b32 s0, s2, 14
	s_add_i32 s0, s0, 0
	v_writelane_b32 v255, s0, 15
	s_and_b32 s0, s5, 0xffffff40
	s_cmp_eq_u32 s0, 0
	s_cselect_b64 s[44:45], -1, 0
	s_bfe_u32 s0, s5, 0x20006
	s_lshl_b32 s76, s0, 5
	s_add_u32 s85, s74, 0x2b400000
	s_addc_u32 s86, s75, 0
	s_lshl_b32 s87, s97, 3
	s_lshl_b32 s1, s97, 2
	s_and_b32 s88, s87, 0x1ffffff0
	s_and_b32 s89, s1, 4
	s_add_u32 s90, s74, 0x23000000
	s_addc_u32 s91, s75, 0
	s_lshl_b32 s0, s0, 14
	s_add_i32 s0, s0, 0
	v_writelane_b32 v255, s0, 21
	s_lshl_b32 s0, s97, 14
	v_writelane_b32 v255, s97, 11
	s_add_i32 s0, s0, 0
	s_lshl_b32 s1, s97, 11
	v_writelane_b32 v255, s0, 7
	s_add_i32 s0, 0, 0x20180
	s_add_i32 s92, s1, 0
	v_writelane_b32 v255, s0, 18
	s_add_i32 s0, 0, 0x207fc
	s_mov_b32 s4, 0x3f803f80
	s_mov_b32 s11, 0
	s_movk_i32 s71, 0xff
	s_add_i32 s93, s92, 0x4000
	v_mov_b32_e32 v211, 0
	s_add_i32 s13, 0, 0x20184
	s_movk_i32 s84, 0x60
	s_add_i32 s35, 0, 0x100fc
	s_mov_b64 s[46:47], 0x4c400800
	v_mov_b32_e32 v214, 0x358637bd
	s_mov_b32 s12, 0xf800000
	v_mov_b32_e32 v215, 0x260
	s_mov_b32 s97, 0x3f4ccccd
	s_mov_b32 s94, 0x4c400000
	s_mov_b64 s[50:51], 0x80
	s_add_i32 s95, 0, 0x204fc
	v_writelane_b32 v255, s0, 19
	s_mov_b32 s5, s4
	s_mov_b32 s6, s4
	s_mov_b32 s7, s4
	s_mov_b32 s15, 0
	s_branch .LBB0_450
